# bf16-store GEMM epilogues: the four bias vectors of a tile requested together (no per-column-group vmcnt(0) drain)
# speedup vs baseline: 1.5941x; 1.0044x over previous
.LBB0_266:
	v_cmp_eq_u64_e32 vcc, 0, v[130:131]
	v_cmp_ne_u64_e64 s[42:43], 0, v[130:131]
	v_lshl_add_u64 v[134:135], v[150:151], 2, v[130:131]
	s_cbranch_vccnz .LBB0_268
	global_load_dwordx4 v[128:131], v[134:135], off
	global_load_dwordx4 v[156:159], v[134:135], off offset:64
	global_load_dwordx4 v[160:163], v[134:135], off offset:512
	global_load_dwordx4 v[164:167], v[134:135], off offset:576
	s_branch .LBB0_269

.LBB0_285:
	v_bfe_u32 v102, v96, 16, 1
	v_add3_u32 v96, v96, v102, s77
	v_bfe_u32 v102, v97, 16, 1
	v_lshrrev_b32_e32 v96, 16, v96
	v_add3_u32 v97, v97, v102, s77
	v_and_or_b32 v96, v97, s35, v96
	v_bfe_u32 v97, v98, 16, 1
	v_add3_u32 v97, v98, v97, s77
	v_bfe_u32 v98, v99, 16, 1
	v_lshrrev_b32_e32 v97, 16, v97
	v_add3_u32 v98, v99, v98, s77
	v_and_or_b32 v97, v98, s35, v97
	v_cndmask_b32_e64 v98, 0, 1, s[42:43]
	v_lshl_add_u64 v[100:101], v[100:101], 0, s[82:83]
	v_cmp_ne_u32_e64 s[40:41], 1, v98
	s_andn2_b64 vcc, exec, s[42:43]
	global_store_dwordx2 v[100:101], v[96:97], off
	s_cbranch_vccnz .LBB0_339
	v_mov_b32_e32 v96, v156
	v_mov_b32_e32 v97, v157
	v_mov_b32_e32 v98, v158
	v_mov_b32_e32 v99, v159
	v_pk_add_f32 v[94:95], v[94:95], v[98:99]
	s_and_b64 vcc, exec, s[38:39]
	v_pk_add_f32 v[92:93], v[92:93], v[96:97]
	s_cbranch_vccnz .LBB0_288

.LBB0_302:
	v_bfe_u32 v70, v64, 16, 1
	v_add3_u32 v64, v64, v70, s77
	v_bfe_u32 v70, v65, 16, 1
	v_lshrrev_b32_e32 v64, 16, v64
	v_add3_u32 v65, v65, v70, s77
	v_and_or_b32 v64, v65, s35, v64
	v_bfe_u32 v65, v66, 16, 1
	v_add3_u32 v65, v66, v65, s77
	v_bfe_u32 v66, v67, 16, 1
	v_lshrrev_b32_e32 v65, 16, v65
	v_add3_u32 v66, v67, v66, s77
	v_and_or_b32 v65, v66, s35, v65
	v_lshl_add_u64 v[68:69], v[68:69], 0, s[82:83]
	s_and_b64 vcc, exec, s[40:41]
	global_store_dwordx2 v[68:69], v[64:65], off offset:32
	s_cbranch_vccnz .LBB0_340
	v_mov_b32_e32 v64, v160
	v_mov_b32_e32 v65, v161
	v_mov_b32_e32 v66, v162
	v_mov_b32_e32 v67, v163
	v_pk_add_f32 v[62:63], v[62:63], v[66:67]
	s_and_b64 vcc, exec, s[38:39]
	v_pk_add_f32 v[60:61], v[60:61], v[64:65]
	s_cbranch_vccnz .LBB0_305

.LBB0_319:
	v_bfe_u32 v38, v32, 16, 1
	v_add3_u32 v32, v32, v38, s77
	v_bfe_u32 v38, v33, 16, 1
	v_lshrrev_b32_e32 v32, 16, v32
	v_add3_u32 v33, v33, v38, s77
	v_and_or_b32 v32, v33, s35, v32
	v_bfe_u32 v33, v34, 16, 1
	v_add3_u32 v33, v34, v33, s77
	v_bfe_u32 v34, v35, 16, 1
	v_lshrrev_b32_e32 v33, 16, v33
	v_add3_u32 v34, v35, v34, s77
	v_and_or_b32 v33, v34, s35, v33
	v_lshl_add_u64 v[36:37], v[36:37], 0, s[82:83]
	s_and_b64 vcc, exec, s[40:41]
	global_store_dwordx2 v[36:37], v[32:33], off offset:256
	s_cbranch_vccnz .LBB0_341
	v_mov_b32_e32 v32, v164
	v_mov_b32_e32 v33, v165
	v_mov_b32_e32 v34, v166
	v_mov_b32_e32 v35, v167
	v_pk_add_f32 v[30:31], v[30:31], v[34:35]
	s_and_b64 vcc, exec, s[38:39]
	v_pk_add_f32 v[28:29], v[28:29], v[32:33]
	s_cbranch_vccnz .LBB0_322
